# P4 copy_caches K/V row loop hand-pipelined: all 16-17 rows of a wave requested up front instead of one exposed round trip per row
# speedup vs baseline: 1.0103x; 1.0103x over previous
.LBB0_508:
	s_or_b64 exec, exec, s[10:11]
	s_waitcnt lgkmcnt(0)
	v_mov_b32_e32 v0, v206
	v_mov_b32_e32 v64, v206
	s_barrier
	s_load_dwordx4 s[40:43], s[0:1], 0x78
	s_load_dwordx2 s[52:53], s[0:1], 0x98
	s_add_u32 s50, s38, 0x11f00000
	s_addc_u32 s51, s39, 0
	s_and_b32 s76, s2, 3
	v_readfirstlane_b32 s10, v64
	s_lshl_b32 s75, s76, 7
	s_ashr_i32 s35, s10, 6
	s_cmpk_gt_i32 s2, 0x7f
	v_and_b32_e32 v66, 63, v64
	s_cbranch_scc0 .LBB0_517
	s_add_i32 s77, s2, 0xffffff80
	s_lshl_b32 s10, s77, 3
	s_add_i32 s26, s34, 0xfffffc00
	s_add_i32 s10, s35, s10
	v_lshlrev_b32_e32 v172, 4, v66
	v_lshlrev_b32_e32 v173, 5, v66
	s_and_b32 s11, s10, 0x1ff
	s_lshr_b32 s12, s10, 9
	s_lshl_b32 s12, s12, 11
	s_add_u32 s12, s12, s11
	s_add_u32 s12, s12, 0x600
	s_mul_i32 s13, s12, 0x2c00
	s_mul_hi_u32 s20, s12, 0x2c00
	s_add_u32 s96, s50, s13
	s_addc_u32 s97, s51, s20
	global_load_dwordx4 v[0:3], v172, s[96:97] offset:1024
	global_load_dwordx4 v[4:7], v172, s[96:97] offset:2048
	s_add_u32 s96, s96, 0x2c00000
	s_addc_u32 s97, s97, 0
	global_load_dwordx4 v[8:11], v172, s[96:97] offset:1024
	global_load_dwordx4 v[12:15], v172, s[96:97] offset:2048
	s_add_u32 s96, s96, 0x2c00000
	s_addc_u32 s97, s97, 0
	global_load_dwordx4 v[16:19], v172, s[96:97] offset:1024
	global_load_dwordx4 v[20:23], v172, s[96:97] offset:2048
	s_add_u32 s96, s96, 0x2c00000
	s_addc_u32 s97, s97, 0
	global_load_dwordx4 v[24:27], v172, s[96:97] offset:1024
	global_load_dwordx4 v[28:31], v172, s[96:97] offset:2048
	s_add_u32 s96, s96, 0x2c00000
	s_addc_u32 s97, s97, 0
	global_load_dwordx4 v[32:35], v172, s[96:97] offset:1024
	global_load_dwordx4 v[36:39], v172, s[96:97] offset:2048
	s_add_u32 s96, s96, 0x2c00000
	s_addc_u32 s97, s97, 0
	global_load_dwordx4 v[40:43], v172, s[96:97] offset:1024
	global_load_dwordx4 v[44:47], v172, s[96:97] offset:2048
	s_add_u32 s96, s96, 0x2c00000
	s_addc_u32 s97, s97, 0
	global_load_dwordx4 v[48:51], v172, s[96:97] offset:1024
	global_load_dwordx4 v[52:55], v172, s[96:97] offset:2048
	s_add_u32 s96, s96, 0x2c00000
	s_addc_u32 s97, s97, 0
	global_load_dwordx4 v[56:59], v172, s[96:97] offset:1024
	global_load_dwordx4 v[60:63], v172, s[96:97] offset:2048
	s_add_u32 s96, s96, 0x2c00000
	s_addc_u32 s97, s97, 0
	global_load_dwordx4 v[68:71], v172, s[96:97] offset:1024
	global_load_dwordx4 v[72:75], v172, s[96:97] offset:2048
	s_add_u32 s96, s96, 0x2c00000
	s_addc_u32 s97, s97, 0
	global_load_dwordx4 v[76:79], v172, s[96:97] offset:1024
	global_load_dwordx4 v[80:83], v172, s[96:97] offset:2048
	s_add_u32 s96, s96, 0x2c00000
	s_addc_u32 s97, s97, 0
	global_load_dwordx4 v[84:87], v172, s[96:97] offset:1024
	global_load_dwordx4 v[88:91], v172, s[96:97] offset:2048
	s_add_u32 s96, s96, 0x2c00000
	s_addc_u32 s97, s97, 0
	global_load_dwordx4 v[92:95], v172, s[96:97] offset:1024
	global_load_dwordx4 v[96:99], v172, s[96:97] offset:2048
	s_add_u32 s96, s96, 0x2c00000
	s_addc_u32 s97, s97, 0
	global_load_dwordx4 v[100:103], v172, s[96:97] offset:1024
	global_load_dwordx4 v[104:107], v172, s[96:97] offset:2048
	s_add_u32 s96, s96, 0x2c00000
	s_addc_u32 s97, s97, 0
	global_load_dwordx4 v[108:111], v172, s[96:97] offset:1024
	global_load_dwordx4 v[112:115], v172, s[96:97] offset:2048
	s_add_u32 s96, s96, 0x2c00000
	s_addc_u32 s97, s97, 0
	global_load_dwordx4 v[116:119], v172, s[96:97] offset:1024
	global_load_dwordx4 v[120:123], v172, s[96:97] offset:2048
	s_add_u32 s96, s96, 0x2c00000
	s_addc_u32 s97, s97, 0
	global_load_dwordx4 v[124:127], v172, s[96:97] offset:1024
	global_load_dwordx4 v[128:131], v172, s[96:97] offset:2048
	s_cmp_lt_u32 s10, 0x100
	s_cbranch_scc0 .Lcc_no17
	s_add_u32 s12, s10, 0x10000
	s_mul_i32 s13, s12, 0x2c00
	s_mul_hi_u32 s20, s12, 0x2c00
	s_add_u32 s96, s50, s13
	s_addc_u32 s97, s51, s20
	global_load_dwordx4 v[132:135], v172, s[96:97] offset:1024
	global_load_dwordx4 v[136:139], v172, s[96:97] offset:2048
.Lcc_no17:
	s_lshl_b32 s13, s10, 11
	s_add_u32 s98, s36, s13
	s_addc_u32 s99, s37, 0
	s_add_u32 s100, s98, 0x12100000
	s_addc_u32 s101, s99, 0
	s_add_u32 s98, s98, 0x10100000
	s_addc_u32 s99, s99, 0
	s_cmp_lt_u32 s10, 0x100
	s_cbranch_scc0 .Lcc_r16
	s_waitcnt vmcnt(33)
	v_lshlrev_b32_e32 v140, 16, v0
	v_and_b32_e32 v141, 0xffff0000, v0
	v_lshlrev_b32_e32 v142, 16, v1
	v_and_b32_e32 v143, 0xffff0000, v1
	v_lshlrev_b32_e32 v144, 16, v2
	v_and_b32_e32 v145, 0xffff0000, v2
	v_lshlrev_b32_e32 v146, 16, v3
	v_and_b32_e32 v147, 0xffff0000, v3
	global_store_dwordx4 v173, v[140:143], s[98:99]
	global_store_dwordx4 v173, v[144:147], s[98:99] offset:16
	s_waitcnt vmcnt(34)
	v_lshlrev_b32_e32 v148, 16, v4
	v_and_b32_e32 v149, 0xffff0000, v4
	v_lshlrev_b32_e32 v150, 16, v5
	v_and_b32_e32 v151, 0xffff0000, v5
	v_lshlrev_b32_e32 v152, 16, v6
	v_and_b32_e32 v153, 0xffff0000, v6
	v_lshlrev_b32_e32 v154, 16, v7
	v_and_b32_e32 v155, 0xffff0000, v7
	global_store_dwordx4 v173, v[148:151], s[100:101]
	global_store_dwordx4 v173, v[152:155], s[100:101] offset:16
	s_add_u32 s98, s98, 0x200000
	s_addc_u32 s99, s99, 0
	s_add_u32 s100, s100, 0x200000
	s_addc_u32 s101, s101, 0
	s_waitcnt vmcnt(35)
	v_lshlrev_b32_e32 v156, 16, v8
	v_and_b32_e32 v157, 0xffff0000, v8
	v_lshlrev_b32_e32 v158, 16, v9
	v_and_b32_e32 v159, 0xffff0000, v9
	v_lshlrev_b32_e32 v160, 16, v10
	v_and_b32_e32 v161, 0xffff0000, v10
	v_lshlrev_b32_e32 v162, 16, v11
	v_and_b32_e32 v163, 0xffff0000, v11
	global_store_dwordx4 v173, v[156:159], s[98:99]
	global_store_dwordx4 v173, v[160:163], s[98:99] offset:16
	s_waitcnt vmcnt(36)
	v_lshlrev_b32_e32 v164, 16, v12
	v_and_b32_e32 v165, 0xffff0000, v12
	v_lshlrev_b32_e32 v166, 16, v13
	v_and_b32_e32 v167, 0xffff0000, v13
	v_lshlrev_b32_e32 v168, 16, v14
	v_and_b32_e32 v169, 0xffff0000, v14
	v_lshlrev_b32_e32 v170, 16, v15
	v_and_b32_e32 v171, 0xffff0000, v15
	global_store_dwordx4 v173, v[164:167], s[100:101]
	global_store_dwordx4 v173, v[168:171], s[100:101] offset:16
	s_add_u32 s98, s98, 0x200000
	s_addc_u32 s99, s99, 0
	s_add_u32 s100, s100, 0x200000
	s_addc_u32 s101, s101, 0
	s_waitcnt vmcnt(37)
	v_lshlrev_b32_e32 v140, 16, v16
	v_and_b32_e32 v141, 0xffff0000, v16
	v_lshlrev_b32_e32 v142, 16, v17
	v_and_b32_e32 v143, 0xffff0000, v17
	v_lshlrev_b32_e32 v144, 16, v18
	v_and_b32_e32 v145, 0xffff0000, v18
	v_lshlrev_b32_e32 v146, 16, v19
	v_and_b32_e32 v147, 0xffff0000, v19
	global_store_dwordx4 v173, v[140:143], s[98:99]
	global_store_dwordx4 v173, v[144:147], s[98:99] offset:16
	s_waitcnt vmcnt(38)
	v_lshlrev_b32_e32 v148, 16, v20
	v_and_b32_e32 v149, 0xffff0000, v20
	v_lshlrev_b32_e32 v150, 16, v21
	v_and_b32_e32 v151, 0xffff0000, v21
	v_lshlrev_b32_e32 v152, 16, v22
	v_and_b32_e32 v153, 0xffff0000, v22
	v_lshlrev_b32_e32 v154, 16, v23
	v_and_b32_e32 v155, 0xffff0000, v23
	global_store_dwordx4 v173, v[148:151], s[100:101]
	global_store_dwordx4 v173, v[152:155], s[100:101] offset:16
	s_add_u32 s98, s98, 0x200000
	s_addc_u32 s99, s99, 0
	s_add_u32 s100, s100, 0x200000
	s_addc_u32 s101, s101, 0
	s_waitcnt vmcnt(39)
	v_lshlrev_b32_e32 v156, 16, v24
	v_and_b32_e32 v157, 0xffff0000, v24
	v_lshlrev_b32_e32 v158, 16, v25
	v_and_b32_e32 v159, 0xffff0000, v25
	v_lshlrev_b32_e32 v160, 16, v26
	v_and_b32_e32 v161, 0xffff0000, v26
	v_lshlrev_b32_e32 v162, 16, v27
	v_and_b32_e32 v163, 0xffff0000, v27
	global_store_dwordx4 v173, v[156:159], s[98:99]
	global_store_dwordx4 v173, v[160:163], s[98:99] offset:16
	s_waitcnt vmcnt(40)
	v_lshlrev_b32_e32 v164, 16, v28
	v_and_b32_e32 v165, 0xffff0000, v28
	v_lshlrev_b32_e32 v166, 16, v29
	v_and_b32_e32 v167, 0xffff0000, v29
	v_lshlrev_b32_e32 v168, 16, v30
	v_and_b32_e32 v169, 0xffff0000, v30
	v_lshlrev_b32_e32 v170, 16, v31
	v_and_b32_e32 v171, 0xffff0000, v31
	global_store_dwordx4 v173, v[164:167], s[100:101]
	global_store_dwordx4 v173, v[168:171], s[100:101] offset:16
	s_add_u32 s98, s98, 0x200000
	s_addc_u32 s99, s99, 0
	s_add_u32 s100, s100, 0x200000
	s_addc_u32 s101, s101, 0
	s_waitcnt vmcnt(41)
	v_lshlrev_b32_e32 v140, 16, v32
	v_and_b32_e32 v141, 0xffff0000, v32
	v_lshlrev_b32_e32 v142, 16, v33
	v_and_b32_e32 v143, 0xffff0000, v33
	v_lshlrev_b32_e32 v144, 16, v34
	v_and_b32_e32 v145, 0xffff0000, v34
	v_lshlrev_b32_e32 v146, 16, v35
	v_and_b32_e32 v147, 0xffff0000, v35
	global_store_dwordx4 v173, v[140:143], s[98:99]
	global_store_dwordx4 v173, v[144:147], s[98:99] offset:16
	s_waitcnt vmcnt(42)
	v_lshlrev_b32_e32 v148, 16, v36
	v_and_b32_e32 v149, 0xffff0000, v36
	v_lshlrev_b32_e32 v150, 16, v37
	v_and_b32_e32 v151, 0xffff0000, v37
	v_lshlrev_b32_e32 v152, 16, v38
	v_and_b32_e32 v153, 0xffff0000, v38
	v_lshlrev_b32_e32 v154, 16, v39
	v_and_b32_e32 v155, 0xffff0000, v39
	global_store_dwordx4 v173, v[148:151], s[100:101]
	global_store_dwordx4 v173, v[152:155], s[100:101] offset:16
	s_add_u32 s98, s98, 0x200000
	s_addc_u32 s99, s99, 0
	s_add_u32 s100, s100, 0x200000
	s_addc_u32 s101, s101, 0
	s_waitcnt vmcnt(43)
	v_lshlrev_b32_e32 v156, 16, v40
	v_and_b32_e32 v157, 0xffff0000, v40
	v_lshlrev_b32_e32 v158, 16, v41
	v_and_b32_e32 v159, 0xffff0000, v41
	v_lshlrev_b32_e32 v160, 16, v42
	v_and_b32_e32 v161, 0xffff0000, v42
	v_lshlrev_b32_e32 v162, 16, v43
	v_and_b32_e32 v163, 0xffff0000, v43
	global_store_dwordx4 v173, v[156:159], s[98:99]
	global_store_dwordx4 v173, v[160:163], s[98:99] offset:16
	s_waitcnt vmcnt(44)
	v_lshlrev_b32_e32 v164, 16, v44
	v_and_b32_e32 v165, 0xffff0000, v44
	v_lshlrev_b32_e32 v166, 16, v45
	v_and_b32_e32 v167, 0xffff0000, v45
	v_lshlrev_b32_e32 v168, 16, v46
	v_and_b32_e32 v169, 0xffff0000, v46
	v_lshlrev_b32_e32 v170, 16, v47
	v_and_b32_e32 v171, 0xffff0000, v47
	global_store_dwordx4 v173, v[164:167], s[100:101]
	global_store_dwordx4 v173, v[168:171], s[100:101] offset:16
	s_add_u32 s98, s98, 0x200000
	s_addc_u32 s99, s99, 0
	s_add_u32 s100, s100, 0x200000
	s_addc_u32 s101, s101, 0
	s_waitcnt vmcnt(45)
	v_lshlrev_b32_e32 v140, 16, v48
	v_and_b32_e32 v141, 0xffff0000, v48
	v_lshlrev_b32_e32 v142, 16, v49
	v_and_b32_e32 v143, 0xffff0000, v49
	v_lshlrev_b32_e32 v144, 16, v50
	v_and_b32_e32 v145, 0xffff0000, v50
	v_lshlrev_b32_e32 v146, 16, v51
	v_and_b32_e32 v147, 0xffff0000, v51
	global_store_dwordx4 v173, v[140:143], s[98:99]
	global_store_dwordx4 v173, v[144:147], s[98:99] offset:16
	s_waitcnt vmcnt(46)
	v_lshlrev_b32_e32 v148, 16, v52
	v_and_b32_e32 v149, 0xffff0000, v52
	v_lshlrev_b32_e32 v150, 16, v53
	v_and_b32_e32 v151, 0xffff0000, v53
	v_lshlrev_b32_e32 v152, 16, v54
	v_and_b32_e32 v153, 0xffff0000, v54
	v_lshlrev_b32_e32 v154, 16, v55
	v_and_b32_e32 v155, 0xffff0000, v55
	global_store_dwordx4 v173, v[148:151], s[100:101]
	global_store_dwordx4 v173, v[152:155], s[100:101] offset:16
	s_add_u32 s98, s98, 0x200000
	s_addc_u32 s99, s99, 0
	s_add_u32 s100, s100, 0x200000
	s_addc_u32 s101, s101, 0
	s_waitcnt vmcnt(47)
	v_lshlrev_b32_e32 v156, 16, v56
	v_and_b32_e32 v157, 0xffff0000, v56
	v_lshlrev_b32_e32 v158, 16, v57
	v_and_b32_e32 v159, 0xffff0000, v57
	v_lshlrev_b32_e32 v160, 16, v58
	v_and_b32_e32 v161, 0xffff0000, v58
	v_lshlrev_b32_e32 v162, 16, v59
	v_and_b32_e32 v163, 0xffff0000, v59
	global_store_dwordx4 v173, v[156:159], s[98:99]
	global_store_dwordx4 v173, v[160:163], s[98:99] offset:16
	s_waitcnt vmcnt(48)
	v_lshlrev_b32_e32 v164, 16, v60
	v_and_b32_e32 v165, 0xffff0000, v60
	v_lshlrev_b32_e32 v166, 16, v61
	v_and_b32_e32 v167, 0xffff0000, v61
	v_lshlrev_b32_e32 v168, 16, v62
	v_and_b32_e32 v169, 0xffff0000, v62
	v_lshlrev_b32_e32 v170, 16, v63
	v_and_b32_e32 v171, 0xffff0000, v63
	global_store_dwordx4 v173, v[164:167], s[100:101]
	global_store_dwordx4 v173, v[168:171], s[100:101] offset:16
	s_add_u32 s98, s98, 0x200000
	s_addc_u32 s99, s99, 0
	s_add_u32 s100, s100, 0x200000
	s_addc_u32 s101, s101, 0
	s_waitcnt vmcnt(49)
	v_lshlrev_b32_e32 v140, 16, v68
	v_and_b32_e32 v141, 0xffff0000, v68
	v_lshlrev_b32_e32 v142, 16, v69
	v_and_b32_e32 v143, 0xffff0000, v69
	v_lshlrev_b32_e32 v144, 16, v70
	v_and_b32_e32 v145, 0xffff0000, v70
	v_lshlrev_b32_e32 v146, 16, v71
	v_and_b32_e32 v147, 0xffff0000, v71
	global_store_dwordx4 v173, v[140:143], s[98:99]
	global_store_dwordx4 v173, v[144:147], s[98:99] offset:16
	s_waitcnt vmcnt(50)
	v_lshlrev_b32_e32 v148, 16, v72
	v_and_b32_e32 v149, 0xffff0000, v72
	v_lshlrev_b32_e32 v150, 16, v73
	v_and_b32_e32 v151, 0xffff0000, v73
	v_lshlrev_b32_e32 v152, 16, v74
	v_and_b32_e32 v153, 0xffff0000, v74
	v_lshlrev_b32_e32 v154, 16, v75
	v_and_b32_e32 v155, 0xffff0000, v75
	global_store_dwordx4 v173, v[148:151], s[100:101]
	global_store_dwordx4 v173, v[152:155], s[100:101] offset:16
	s_add_u32 s98, s98, 0x200000
	s_addc_u32 s99, s99, 0
	s_add_u32 s100, s100, 0x200000
	s_addc_u32 s101, s101, 0
	s_waitcnt vmcnt(51)
	v_lshlrev_b32_e32 v156, 16, v76
	v_and_b32_e32 v157, 0xffff0000, v76
	v_lshlrev_b32_e32 v158, 16, v77
	v_and_b32_e32 v159, 0xffff0000, v77
	v_lshlrev_b32_e32 v160, 16, v78
	v_and_b32_e32 v161, 0xffff0000, v78
	v_lshlrev_b32_e32 v162, 16, v79
	v_and_b32_e32 v163, 0xffff0000, v79
	global_store_dwordx4 v173, v[156:159], s[98:99]
	global_store_dwordx4 v173, v[160:163], s[98:99] offset:16
	s_waitcnt vmcnt(52)
	v_lshlrev_b32_e32 v164, 16, v80
	v_and_b32_e32 v165, 0xffff0000, v80
	v_lshlrev_b32_e32 v166, 16, v81
	v_and_b32_e32 v167, 0xffff0000, v81
	v_lshlrev_b32_e32 v168, 16, v82
	v_and_b32_e32 v169, 0xffff0000, v82
	v_lshlrev_b32_e32 v170, 16, v83
	v_and_b32_e32 v171, 0xffff0000, v83
	global_store_dwordx4 v173, v[164:167], s[100:101]
	global_store_dwordx4 v173, v[168:171], s[100:101] offset:16
	s_add_u32 s98, s98, 0x200000
	s_addc_u32 s99, s99, 0
	s_add_u32 s100, s100, 0x200000
	s_addc_u32 s101, s101, 0
	s_waitcnt vmcnt(53)
	v_lshlrev_b32_e32 v140, 16, v84
	v_and_b32_e32 v141, 0xffff0000, v84
	v_lshlrev_b32_e32 v142, 16, v85
	v_and_b32_e32 v143, 0xffff0000, v85
	v_lshlrev_b32_e32 v144, 16, v86
	v_and_b32_e32 v145, 0xffff0000, v86
	v_lshlrev_b32_e32 v146, 16, v87
	v_and_b32_e32 v147, 0xffff0000, v87
	global_store_dwordx4 v173, v[140:143], s[98:99]
	global_store_dwordx4 v173, v[144:147], s[98:99] offset:16
	s_waitcnt vmcnt(54)
	v_lshlrev_b32_e32 v148, 16, v88
	v_and_b32_e32 v149, 0xffff0000, v88
	v_lshlrev_b32_e32 v150, 16, v89
	v_and_b32_e32 v151, 0xffff0000, v89
	v_lshlrev_b32_e32 v152, 16, v90
	v_and_b32_e32 v153, 0xffff0000, v90
	v_lshlrev_b32_e32 v154, 16, v91
	v_and_b32_e32 v155, 0xffff0000, v91
	global_store_dwordx4 v173, v[148:151], s[100:101]
	global_store_dwordx4 v173, v[152:155], s[100:101] offset:16
	s_add_u32 s98, s98, 0x200000
	s_addc_u32 s99, s99, 0
	s_add_u32 s100, s100, 0x200000
	s_addc_u32 s101, s101, 0
	s_waitcnt vmcnt(55)
	v_lshlrev_b32_e32 v156, 16, v92
	v_and_b32_e32 v157, 0xffff0000, v92
	v_lshlrev_b32_e32 v158, 16, v93
	v_and_b32_e32 v159, 0xffff0000, v93
	v_lshlrev_b32_e32 v160, 16, v94
	v_and_b32_e32 v161, 0xffff0000, v94
	v_lshlrev_b32_e32 v162, 16, v95
	v_and_b32_e32 v163, 0xffff0000, v95
	global_store_dwordx4 v173, v[156:159], s[98:99]
	global_store_dwordx4 v173, v[160:163], s[98:99] offset:16
	s_waitcnt vmcnt(56)
	v_lshlrev_b32_e32 v164, 16, v96
	v_and_b32_e32 v165, 0xffff0000, v96
	v_lshlrev_b32_e32 v166, 16, v97
	v_and_b32_e32 v167, 0xffff0000, v97
	v_lshlrev_b32_e32 v168, 16, v98
	v_and_b32_e32 v169, 0xffff0000, v98
	v_lshlrev_b32_e32 v170, 16, v99
	v_and_b32_e32 v171, 0xffff0000, v99
	global_store_dwordx4 v173, v[164:167], s[100:101]
	global_store_dwordx4 v173, v[168:171], s[100:101] offset:16
	s_add_u32 s98, s98, 0x200000
	s_addc_u32 s99, s99, 0
	s_add_u32 s100, s100, 0x200000
	s_addc_u32 s101, s101, 0
	s_waitcnt vmcnt(57)
	v_lshlrev_b32_e32 v140, 16, v100
	v_and_b32_e32 v141, 0xffff0000, v100
	v_lshlrev_b32_e32 v142, 16, v101
	v_and_b32_e32 v143, 0xffff0000, v101
	v_lshlrev_b32_e32 v144, 16, v102
	v_and_b32_e32 v145, 0xffff0000, v102
	v_lshlrev_b32_e32 v146, 16, v103
	v_and_b32_e32 v147, 0xffff0000, v103
	global_store_dwordx4 v173, v[140:143], s[98:99]
	global_store_dwordx4 v173, v[144:147], s[98:99] offset:16
	s_waitcnt vmcnt(58)
	v_lshlrev_b32_e32 v148, 16, v104
	v_and_b32_e32 v149, 0xffff0000, v104
	v_lshlrev_b32_e32 v150, 16, v105
	v_and_b32_e32 v151, 0xffff0000, v105
	v_lshlrev_b32_e32 v152, 16, v106
	v_and_b32_e32 v153, 0xffff0000, v106
	v_lshlrev_b32_e32 v154, 16, v107
	v_and_b32_e32 v155, 0xffff0000, v107
	global_store_dwordx4 v173, v[148:151], s[100:101]
	global_store_dwordx4 v173, v[152:155], s[100:101] offset:16
	s_add_u32 s98, s98, 0x200000
	s_addc_u32 s99, s99, 0
	s_add_u32 s100, s100, 0x200000
	s_addc_u32 s101, s101, 0
	s_waitcnt vmcnt(59)
	v_lshlrev_b32_e32 v156, 16, v108
	v_and_b32_e32 v157, 0xffff0000, v108
	v_lshlrev_b32_e32 v158, 16, v109
	v_and_b32_e32 v159, 0xffff0000, v109
	v_lshlrev_b32_e32 v160, 16, v110
	v_and_b32_e32 v161, 0xffff0000, v110
	v_lshlrev_b32_e32 v162, 16, v111
	v_and_b32_e32 v163, 0xffff0000, v111
	global_store_dwordx4 v173, v[156:159], s[98:99]
	global_store_dwordx4 v173, v[160:163], s[98:99] offset:16
	s_waitcnt vmcnt(60)
	v_lshlrev_b32_e32 v164, 16, v112
	v_and_b32_e32 v165, 0xffff0000, v112
	v_lshlrev_b32_e32 v166, 16, v113
	v_and_b32_e32 v167, 0xffff0000, v113
	v_lshlrev_b32_e32 v168, 16, v114
	v_and_b32_e32 v169, 0xffff0000, v114
	v_lshlrev_b32_e32 v170, 16, v115
	v_and_b32_e32 v171, 0xffff0000, v115
	global_store_dwordx4 v173, v[164:167], s[100:101]
	global_store_dwordx4 v173, v[168:171], s[100:101] offset:16
	s_add_u32 s98, s98, 0x200000
	s_addc_u32 s99, s99, 0
	s_add_u32 s100, s100, 0x200000
	s_addc_u32 s101, s101, 0
	s_waitcnt vmcnt(61)
	v_lshlrev_b32_e32 v140, 16, v116
	v_and_b32_e32 v141, 0xffff0000, v116
	v_lshlrev_b32_e32 v142, 16, v117
	v_and_b32_e32 v143, 0xffff0000, v117
	v_lshlrev_b32_e32 v144, 16, v118
	v_and_b32_e32 v145, 0xffff0000, v118
	v_lshlrev_b32_e32 v146, 16, v119
	v_and_b32_e32 v147, 0xffff0000, v119
	global_store_dwordx4 v173, v[140:143], s[98:99]
	global_store_dwordx4 v173, v[144:147], s[98:99] offset:16
	s_waitcnt vmcnt(62)
	v_lshlrev_b32_e32 v148, 16, v120
	v_and_b32_e32 v149, 0xffff0000, v120
	v_lshlrev_b32_e32 v150, 16, v121
	v_and_b32_e32 v151, 0xffff0000, v121
	v_lshlrev_b32_e32 v152, 16, v122
	v_and_b32_e32 v153, 0xffff0000, v122
	v_lshlrev_b32_e32 v154, 16, v123
	v_and_b32_e32 v155, 0xffff0000, v123
	global_store_dwordx4 v173, v[148:151], s[100:101]
	global_store_dwordx4 v173, v[152:155], s[100:101] offset:16
	s_add_u32 s98, s98, 0x200000
	s_addc_u32 s99, s99, 0
	s_add_u32 s100, s100, 0x200000
	s_addc_u32 s101, s101, 0
	s_waitcnt vmcnt(63)
	v_lshlrev_b32_e32 v156, 16, v124
	v_and_b32_e32 v157, 0xffff0000, v124
	v_lshlrev_b32_e32 v158, 16, v125
	v_and_b32_e32 v159, 0xffff0000, v125
	v_lshlrev_b32_e32 v160, 16, v126
	v_and_b32_e32 v161, 0xffff0000, v126
	v_lshlrev_b32_e32 v162, 16, v127
	v_and_b32_e32 v163, 0xffff0000, v127
	global_store_dwordx4 v173, v[156:159], s[98:99]
	global_store_dwordx4 v173, v[160:163], s[98:99] offset:16
	s_waitcnt vmcnt(63)
	v_lshlrev_b32_e32 v164, 16, v128
	v_and_b32_e32 v165, 0xffff0000, v128
	v_lshlrev_b32_e32 v166, 16, v129
	v_and_b32_e32 v167, 0xffff0000, v129
	v_lshlrev_b32_e32 v168, 16, v130
	v_and_b32_e32 v169, 0xffff0000, v130
	v_lshlrev_b32_e32 v170, 16, v131
	v_and_b32_e32 v171, 0xffff0000, v131
	global_store_dwordx4 v173, v[164:167], s[100:101]
	global_store_dwordx4 v173, v[168:171], s[100:101] offset:16
	s_lshl_b32 s13, s10, 11
	s_add_u32 s98, s36, s13
	s_addc_u32 s99, s37, 0
	s_add_u32 s100, s98, 0x18a10000
	s_addc_u32 s101, s99, 0
	s_add_u32 s98, s98, 0x18990000
	s_addc_u32 s99, s99, 0
	s_waitcnt vmcnt(0)
	v_lshlrev_b32_e32 v140, 16, v132
	v_and_b32_e32 v141, 0xffff0000, v132
	v_lshlrev_b32_e32 v142, 16, v133
	v_and_b32_e32 v143, 0xffff0000, v133
	v_lshlrev_b32_e32 v144, 16, v134
	v_and_b32_e32 v145, 0xffff0000, v134
	v_lshlrev_b32_e32 v146, 16, v135
	v_and_b32_e32 v147, 0xffff0000, v135
	global_store_dwordx4 v173, v[140:143], s[98:99]
	global_store_dwordx4 v173, v[144:147], s[98:99] offset:16
	v_lshlrev_b32_e32 v148, 16, v136
	v_and_b32_e32 v149, 0xffff0000, v136
	v_lshlrev_b32_e32 v150, 16, v137
	v_and_b32_e32 v151, 0xffff0000, v137
	v_lshlrev_b32_e32 v152, 16, v138
	v_and_b32_e32 v153, 0xffff0000, v138
	v_lshlrev_b32_e32 v154, 16, v139
	v_and_b32_e32 v155, 0xffff0000, v139
	global_store_dwordx4 v173, v[148:151], s[100:101]
	global_store_dwordx4 v173, v[152:155], s[100:101] offset:16
	s_branch .Lcc_done
.Lcc_r16:
	s_waitcnt vmcnt(31)
	v_lshlrev_b32_e32 v156, 16, v0
	v_and_b32_e32 v157, 0xffff0000, v0
	v_lshlrev_b32_e32 v158, 16, v1
	v_and_b32_e32 v159, 0xffff0000, v1
	v_lshlrev_b32_e32 v160, 16, v2
	v_and_b32_e32 v161, 0xffff0000, v2
	v_lshlrev_b32_e32 v162, 16, v3
	v_and_b32_e32 v163, 0xffff0000, v3
	global_store_dwordx4 v173, v[156:159], s[98:99]
	global_store_dwordx4 v173, v[160:163], s[98:99] offset:16
	s_waitcnt vmcnt(32)
	v_lshlrev_b32_e32 v164, 16, v4
	v_and_b32_e32 v165, 0xffff0000, v4
	v_lshlrev_b32_e32 v166, 16, v5
	v_and_b32_e32 v167, 0xffff0000, v5
	v_lshlrev_b32_e32 v168, 16, v6
	v_and_b32_e32 v169, 0xffff0000, v6
	v_lshlrev_b32_e32 v170, 16, v7
	v_and_b32_e32 v171, 0xffff0000, v7
	global_store_dwordx4 v173, v[164:167], s[100:101]
	global_store_dwordx4 v173, v[168:171], s[100:101] offset:16
	s_add_u32 s98, s98, 0x200000
	s_addc_u32 s99, s99, 0
	s_add_u32 s100, s100, 0x200000
	s_addc_u32 s101, s101, 0
	s_waitcnt vmcnt(33)
	v_lshlrev_b32_e32 v140, 16, v8
	v_and_b32_e32 v141, 0xffff0000, v8
	v_lshlrev_b32_e32 v142, 16, v9
	v_and_b32_e32 v143, 0xffff0000, v9
	v_lshlrev_b32_e32 v144, 16, v10
	v_and_b32_e32 v145, 0xffff0000, v10
	v_lshlrev_b32_e32 v146, 16, v11
	v_and_b32_e32 v147, 0xffff0000, v11
	global_store_dwordx4 v173, v[140:143], s[98:99]
	global_store_dwordx4 v173, v[144:147], s[98:99] offset:16
	s_waitcnt vmcnt(34)
	v_lshlrev_b32_e32 v148, 16, v12
	v_and_b32_e32 v149, 0xffff0000, v12
	v_lshlrev_b32_e32 v150, 16, v13
	v_and_b32_e32 v151, 0xffff0000, v13
	v_lshlrev_b32_e32 v152, 16, v14
	v_and_b32_e32 v153, 0xffff0000, v14
	v_lshlrev_b32_e32 v154, 16, v15
	v_and_b32_e32 v155, 0xffff0000, v15
	global_store_dwordx4 v173, v[148:151], s[100:101]
	global_store_dwordx4 v173, v[152:155], s[100:101] offset:16
	s_add_u32 s98, s98, 0x200000
	s_addc_u32 s99, s99, 0
	s_add_u32 s100, s100, 0x200000
	s_addc_u32 s101, s101, 0
	s_waitcnt vmcnt(35)
	v_lshlrev_b32_e32 v156, 16, v16
	v_and_b32_e32 v157, 0xffff0000, v16
	v_lshlrev_b32_e32 v158, 16, v17
	v_and_b32_e32 v159, 0xffff0000, v17
	v_lshlrev_b32_e32 v160, 16, v18
	v_and_b32_e32 v161, 0xffff0000, v18
	v_lshlrev_b32_e32 v162, 16, v19
	v_and_b32_e32 v163, 0xffff0000, v19
	global_store_dwordx4 v173, v[156:159], s[98:99]
	global_store_dwordx4 v173, v[160:163], s[98:99] offset:16
	s_waitcnt vmcnt(36)
	v_lshlrev_b32_e32 v164, 16, v20
	v_and_b32_e32 v165, 0xffff0000, v20
	v_lshlrev_b32_e32 v166, 16, v21
	v_and_b32_e32 v167, 0xffff0000, v21
	v_lshlrev_b32_e32 v168, 16, v22
	v_and_b32_e32 v169, 0xffff0000, v22
	v_lshlrev_b32_e32 v170, 16, v23
	v_and_b32_e32 v171, 0xffff0000, v23
	global_store_dwordx4 v173, v[164:167], s[100:101]
	global_store_dwordx4 v173, v[168:171], s[100:101] offset:16
	s_add_u32 s98, s98, 0x200000
	s_addc_u32 s99, s99, 0
	s_add_u32 s100, s100, 0x200000
	s_addc_u32 s101, s101, 0
	s_waitcnt vmcnt(37)
	v_lshlrev_b32_e32 v140, 16, v24
	v_and_b32_e32 v141, 0xffff0000, v24
	v_lshlrev_b32_e32 v142, 16, v25
	v_and_b32_e32 v143, 0xffff0000, v25
	v_lshlrev_b32_e32 v144, 16, v26
	v_and_b32_e32 v145, 0xffff0000, v26
	v_lshlrev_b32_e32 v146, 16, v27
	v_and_b32_e32 v147, 0xffff0000, v27
	global_store_dwordx4 v173, v[140:143], s[98:99]
	global_store_dwordx4 v173, v[144:147], s[98:99] offset:16
	s_waitcnt vmcnt(38)
	v_lshlrev_b32_e32 v148, 16, v28
	v_and_b32_e32 v149, 0xffff0000, v28
	v_lshlrev_b32_e32 v150, 16, v29
	v_and_b32_e32 v151, 0xffff0000, v29
	v_lshlrev_b32_e32 v152, 16, v30
	v_and_b32_e32 v153, 0xffff0000, v30
	v_lshlrev_b32_e32 v154, 16, v31
	v_and_b32_e32 v155, 0xffff0000, v31
	global_store_dwordx4 v173, v[148:151], s[100:101]
	global_store_dwordx4 v173, v[152:155], s[100:101] offset:16
	s_add_u32 s98, s98, 0x200000
	s_addc_u32 s99, s99, 0
	s_add_u32 s100, s100, 0x200000
	s_addc_u32 s101, s101, 0
	s_waitcnt vmcnt(39)
	v_lshlrev_b32_e32 v156, 16, v32
	v_and_b32_e32 v157, 0xffff0000, v32
	v_lshlrev_b32_e32 v158, 16, v33
	v_and_b32_e32 v159, 0xffff0000, v33
	v_lshlrev_b32_e32 v160, 16, v34
	v_and_b32_e32 v161, 0xffff0000, v34
	v_lshlrev_b32_e32 v162, 16, v35
	v_and_b32_e32 v163, 0xffff0000, v35
	global_store_dwordx4 v173, v[156:159], s[98:99]
	global_store_dwordx4 v173, v[160:163], s[98:99] offset:16
	s_waitcnt vmcnt(40)
	v_lshlrev_b32_e32 v164, 16, v36
	v_and_b32_e32 v165, 0xffff0000, v36
	v_lshlrev_b32_e32 v166, 16, v37
	v_and_b32_e32 v167, 0xffff0000, v37
	v_lshlrev_b32_e32 v168, 16, v38
	v_and_b32_e32 v169, 0xffff0000, v38
	v_lshlrev_b32_e32 v170, 16, v39
	v_and_b32_e32 v171, 0xffff0000, v39
	global_store_dwordx4 v173, v[164:167], s[100:101]
	global_store_dwordx4 v173, v[168:171], s[100:101] offset:16
	s_add_u32 s98, s98, 0x200000
	s_addc_u32 s99, s99, 0
	s_add_u32 s100, s100, 0x200000
	s_addc_u32 s101, s101, 0
	s_waitcnt vmcnt(41)
	v_lshlrev_b32_e32 v140, 16, v40
	v_and_b32_e32 v141, 0xffff0000, v40
	v_lshlrev_b32_e32 v142, 16, v41
	v_and_b32_e32 v143, 0xffff0000, v41
	v_lshlrev_b32_e32 v144, 16, v42
	v_and_b32_e32 v145, 0xffff0000, v42
	v_lshlrev_b32_e32 v146, 16, v43
	v_and_b32_e32 v147, 0xffff0000, v43
	global_store_dwordx4 v173, v[140:143], s[98:99]
	global_store_dwordx4 v173, v[144:147], s[98:99] offset:16
	s_waitcnt vmcnt(42)
	v_lshlrev_b32_e32 v148, 16, v44
	v_and_b32_e32 v149, 0xffff0000, v44
	v_lshlrev_b32_e32 v150, 16, v45
	v_and_b32_e32 v151, 0xffff0000, v45
	v_lshlrev_b32_e32 v152, 16, v46
	v_and_b32_e32 v153, 0xffff0000, v46
	v_lshlrev_b32_e32 v154, 16, v47
	v_and_b32_e32 v155, 0xffff0000, v47
	global_store_dwordx4 v173, v[148:151], s[100:101]
	global_store_dwordx4 v173, v[152:155], s[100:101] offset:16
	s_add_u32 s98, s98, 0x200000
	s_addc_u32 s99, s99, 0
	s_add_u32 s100, s100, 0x200000
	s_addc_u32 s101, s101, 0
	s_waitcnt vmcnt(43)
	v_lshlrev_b32_e32 v156, 16, v48
	v_and_b32_e32 v157, 0xffff0000, v48
	v_lshlrev_b32_e32 v158, 16, v49
	v_and_b32_e32 v159, 0xffff0000, v49
	v_lshlrev_b32_e32 v160, 16, v50
	v_and_b32_e32 v161, 0xffff0000, v50
	v_lshlrev_b32_e32 v162, 16, v51
	v_and_b32_e32 v163, 0xffff0000, v51
	global_store_dwordx4 v173, v[156:159], s[98:99]
	global_store_dwordx4 v173, v[160:163], s[98:99] offset:16
	s_waitcnt vmcnt(44)
	v_lshlrev_b32_e32 v164, 16, v52
	v_and_b32_e32 v165, 0xffff0000, v52
	v_lshlrev_b32_e32 v166, 16, v53
	v_and_b32_e32 v167, 0xffff0000, v53
	v_lshlrev_b32_e32 v168, 16, v54
	v_and_b32_e32 v169, 0xffff0000, v54
	v_lshlrev_b32_e32 v170, 16, v55
	v_and_b32_e32 v171, 0xffff0000, v55
	global_store_dwordx4 v173, v[164:167], s[100:101]
	global_store_dwordx4 v173, v[168:171], s[100:101] offset:16
	s_add_u32 s98, s98, 0x200000
	s_addc_u32 s99, s99, 0
	s_add_u32 s100, s100, 0x200000
	s_addc_u32 s101, s101, 0
	s_waitcnt vmcnt(45)
	v_lshlrev_b32_e32 v140, 16, v56
	v_and_b32_e32 v141, 0xffff0000, v56
	v_lshlrev_b32_e32 v142, 16, v57
	v_and_b32_e32 v143, 0xffff0000, v57
	v_lshlrev_b32_e32 v144, 16, v58
	v_and_b32_e32 v145, 0xffff0000, v58
	v_lshlrev_b32_e32 v146, 16, v59
	v_and_b32_e32 v147, 0xffff0000, v59
	global_store_dwordx4 v173, v[140:143], s[98:99]
	global_store_dwordx4 v173, v[144:147], s[98:99] offset:16
	s_waitcnt vmcnt(46)
	v_lshlrev_b32_e32 v148, 16, v60
	v_and_b32_e32 v149, 0xffff0000, v60
	v_lshlrev_b32_e32 v150, 16, v61
	v_and_b32_e32 v151, 0xffff0000, v61
	v_lshlrev_b32_e32 v152, 16, v62
	v_and_b32_e32 v153, 0xffff0000, v62
	v_lshlrev_b32_e32 v154, 16, v63
	v_and_b32_e32 v155, 0xffff0000, v63
	global_store_dwordx4 v173, v[148:151], s[100:101]
	global_store_dwordx4 v173, v[152:155], s[100:101] offset:16
	s_add_u32 s98, s98, 0x200000
	s_addc_u32 s99, s99, 0
	s_add_u32 s100, s100, 0x200000
	s_addc_u32 s101, s101, 0
	s_waitcnt vmcnt(47)
	v_lshlrev_b32_e32 v156, 16, v68
	v_and_b32_e32 v157, 0xffff0000, v68
	v_lshlrev_b32_e32 v158, 16, v69
	v_and_b32_e32 v159, 0xffff0000, v69
	v_lshlrev_b32_e32 v160, 16, v70
	v_and_b32_e32 v161, 0xffff0000, v70
	v_lshlrev_b32_e32 v162, 16, v71
	v_and_b32_e32 v163, 0xffff0000, v71
	global_store_dwordx4 v173, v[156:159], s[98:99]
	global_store_dwordx4 v173, v[160:163], s[98:99] offset:16
	s_waitcnt vmcnt(48)
	v_lshlrev_b32_e32 v164, 16, v72
	v_and_b32_e32 v165, 0xffff0000, v72
	v_lshlrev_b32_e32 v166, 16, v73
	v_and_b32_e32 v167, 0xffff0000, v73
	v_lshlrev_b32_e32 v168, 16, v74
	v_and_b32_e32 v169, 0xffff0000, v74
	v_lshlrev_b32_e32 v170, 16, v75
	v_and_b32_e32 v171, 0xffff0000, v75
	global_store_dwordx4 v173, v[164:167], s[100:101]
	global_store_dwordx4 v173, v[168:171], s[100:101] offset:16
	s_add_u32 s98, s98, 0x200000
	s_addc_u32 s99, s99, 0
	s_add_u32 s100, s100, 0x200000
	s_addc_u32 s101, s101, 0
	s_waitcnt vmcnt(49)
	v_lshlrev_b32_e32 v140, 16, v76
	v_and_b32_e32 v141, 0xffff0000, v76
	v_lshlrev_b32_e32 v142, 16, v77
	v_and_b32_e32 v143, 0xffff0000, v77
	v_lshlrev_b32_e32 v144, 16, v78
	v_and_b32_e32 v145, 0xffff0000, v78
	v_lshlrev_b32_e32 v146, 16, v79
	v_and_b32_e32 v147, 0xffff0000, v79
	global_store_dwordx4 v173, v[140:143], s[98:99]
	global_store_dwordx4 v173, v[144:147], s[98:99] offset:16
	s_waitcnt vmcnt(50)
	v_lshlrev_b32_e32 v148, 16, v80
	v_and_b32_e32 v149, 0xffff0000, v80
	v_lshlrev_b32_e32 v150, 16, v81
	v_and_b32_e32 v151, 0xffff0000, v81
	v_lshlrev_b32_e32 v152, 16, v82
	v_and_b32_e32 v153, 0xffff0000, v82
	v_lshlrev_b32_e32 v154, 16, v83
	v_and_b32_e32 v155, 0xffff0000, v83
	global_store_dwordx4 v173, v[148:151], s[100:101]
	global_store_dwordx4 v173, v[152:155], s[100:101] offset:16
	s_add_u32 s98, s98, 0x200000
	s_addc_u32 s99, s99, 0
	s_add_u32 s100, s100, 0x200000
	s_addc_u32 s101, s101, 0
	s_waitcnt vmcnt(51)
	v_lshlrev_b32_e32 v156, 16, v84
	v_and_b32_e32 v157, 0xffff0000, v84
	v_lshlrev_b32_e32 v158, 16, v85
	v_and_b32_e32 v159, 0xffff0000, v85
	v_lshlrev_b32_e32 v160, 16, v86
	v_and_b32_e32 v161, 0xffff0000, v86
	v_lshlrev_b32_e32 v162, 16, v87
	v_and_b32_e32 v163, 0xffff0000, v87
	global_store_dwordx4 v173, v[156:159], s[98:99]
	global_store_dwordx4 v173, v[160:163], s[98:99] offset:16
	s_waitcnt vmcnt(52)
	v_lshlrev_b32_e32 v164, 16, v88
	v_and_b32_e32 v165, 0xffff0000, v88
	v_lshlrev_b32_e32 v166, 16, v89
	v_and_b32_e32 v167, 0xffff0000, v89
	v_lshlrev_b32_e32 v168, 16, v90
	v_and_b32_e32 v169, 0xffff0000, v90
	v_lshlrev_b32_e32 v170, 16, v91
	v_and_b32_e32 v171, 0xffff0000, v91
	global_store_dwordx4 v173, v[164:167], s[100:101]
	global_store_dwordx4 v173, v[168:171], s[100:101] offset:16
	s_add_u32 s98, s98, 0x200000
	s_addc_u32 s99, s99, 0
	s_add_u32 s100, s100, 0x200000
	s_addc_u32 s101, s101, 0
	s_waitcnt vmcnt(53)
	v_lshlrev_b32_e32 v140, 16, v92
	v_and_b32_e32 v141, 0xffff0000, v92
	v_lshlrev_b32_e32 v142, 16, v93
	v_and_b32_e32 v143, 0xffff0000, v93
	v_lshlrev_b32_e32 v144, 16, v94
	v_and_b32_e32 v145, 0xffff0000, v94
	v_lshlrev_b32_e32 v146, 16, v95
	v_and_b32_e32 v147, 0xffff0000, v95
	global_store_dwordx4 v173, v[140:143], s[98:99]
	global_store_dwordx4 v173, v[144:147], s[98:99] offset:16
	s_waitcnt vmcnt(54)
	v_lshlrev_b32_e32 v148, 16, v96
	v_and_b32_e32 v149, 0xffff0000, v96
	v_lshlrev_b32_e32 v150, 16, v97
	v_and_b32_e32 v151, 0xffff0000, v97
	v_lshlrev_b32_e32 v152, 16, v98
	v_and_b32_e32 v153, 0xffff0000, v98
	v_lshlrev_b32_e32 v154, 16, v99
	v_and_b32_e32 v155, 0xffff0000, v99
	global_store_dwordx4 v173, v[148:151], s[100:101]
	global_store_dwordx4 v173, v[152:155], s[100:101] offset:16
	s_add_u32 s98, s98, 0x200000
	s_addc_u32 s99, s99, 0
	s_add_u32 s100, s100, 0x200000
	s_addc_u32 s101, s101, 0
	s_waitcnt vmcnt(55)
	v_lshlrev_b32_e32 v156, 16, v100
	v_and_b32_e32 v157, 0xffff0000, v100
	v_lshlrev_b32_e32 v158, 16, v101
	v_and_b32_e32 v159, 0xffff0000, v101
	v_lshlrev_b32_e32 v160, 16, v102
	v_and_b32_e32 v161, 0xffff0000, v102
	v_lshlrev_b32_e32 v162, 16, v103
	v_and_b32_e32 v163, 0xffff0000, v103
	global_store_dwordx4 v173, v[156:159], s[98:99]
	global_store_dwordx4 v173, v[160:163], s[98:99] offset:16
	s_waitcnt vmcnt(56)
	v_lshlrev_b32_e32 v164, 16, v104
	v_and_b32_e32 v165, 0xffff0000, v104
	v_lshlrev_b32_e32 v166, 16, v105
	v_and_b32_e32 v167, 0xffff0000, v105
	v_lshlrev_b32_e32 v168, 16, v106
	v_and_b32_e32 v169, 0xffff0000, v106
	v_lshlrev_b32_e32 v170, 16, v107
	v_and_b32_e32 v171, 0xffff0000, v107
	global_store_dwordx4 v173, v[164:167], s[100:101]
	global_store_dwordx4 v173, v[168:171], s[100:101] offset:16
	s_add_u32 s98, s98, 0x200000
	s_addc_u32 s99, s99, 0
	s_add_u32 s100, s100, 0x200000
	s_addc_u32 s101, s101, 0
	s_waitcnt vmcnt(57)
	v_lshlrev_b32_e32 v140, 16, v108
	v_and_b32_e32 v141, 0xffff0000, v108
	v_lshlrev_b32_e32 v142, 16, v109
	v_and_b32_e32 v143, 0xffff0000, v109
	v_lshlrev_b32_e32 v144, 16, v110
	v_and_b32_e32 v145, 0xffff0000, v110
	v_lshlrev_b32_e32 v146, 16, v111
	v_and_b32_e32 v147, 0xffff0000, v111
	global_store_dwordx4 v173, v[140:143], s[98:99]
	global_store_dwordx4 v173, v[144:147], s[98:99] offset:16
	s_waitcnt vmcnt(58)
	v_lshlrev_b32_e32 v148, 16, v112
	v_and_b32_e32 v149, 0xffff0000, v112
	v_lshlrev_b32_e32 v150, 16, v113
	v_and_b32_e32 v151, 0xffff0000, v113
	v_lshlrev_b32_e32 v152, 16, v114
	v_and_b32_e32 v153, 0xffff0000, v114
	v_lshlrev_b32_e32 v154, 16, v115
	v_and_b32_e32 v155, 0xffff0000, v115
	global_store_dwordx4 v173, v[148:151], s[100:101]
	global_store_dwordx4 v173, v[152:155], s[100:101] offset:16
	s_add_u32 s98, s98, 0x200000
	s_addc_u32 s99, s99, 0
	s_add_u32 s100, s100, 0x200000
	s_addc_u32 s101, s101, 0
	s_waitcnt vmcnt(59)
	v_lshlrev_b32_e32 v156, 16, v116
	v_and_b32_e32 v157, 0xffff0000, v116
	v_lshlrev_b32_e32 v158, 16, v117
	v_and_b32_e32 v159, 0xffff0000, v117
	v_lshlrev_b32_e32 v160, 16, v118
	v_and_b32_e32 v161, 0xffff0000, v118
	v_lshlrev_b32_e32 v162, 16, v119
	v_and_b32_e32 v163, 0xffff0000, v119
	global_store_dwordx4 v173, v[156:159], s[98:99]
	global_store_dwordx4 v173, v[160:163], s[98:99] offset:16
	s_waitcnt vmcnt(60)
	v_lshlrev_b32_e32 v164, 16, v120
	v_and_b32_e32 v165, 0xffff0000, v120
	v_lshlrev_b32_e32 v166, 16, v121
	v_and_b32_e32 v167, 0xffff0000, v121
	v_lshlrev_b32_e32 v168, 16, v122
	v_and_b32_e32 v169, 0xffff0000, v122
	v_lshlrev_b32_e32 v170, 16, v123
	v_and_b32_e32 v171, 0xffff0000, v123
	global_store_dwordx4 v173, v[164:167], s[100:101]
	global_store_dwordx4 v173, v[168:171], s[100:101] offset:16
	s_add_u32 s98, s98, 0x200000
	s_addc_u32 s99, s99, 0
	s_add_u32 s100, s100, 0x200000
	s_addc_u32 s101, s101, 0
	s_waitcnt vmcnt(61)
	v_lshlrev_b32_e32 v140, 16, v124
	v_and_b32_e32 v141, 0xffff0000, v124
	v_lshlrev_b32_e32 v142, 16, v125
	v_and_b32_e32 v143, 0xffff0000, v125
	v_lshlrev_b32_e32 v144, 16, v126
	v_and_b32_e32 v145, 0xffff0000, v126
	v_lshlrev_b32_e32 v146, 16, v127
	v_and_b32_e32 v147, 0xffff0000, v127
	global_store_dwordx4 v173, v[140:143], s[98:99]
	global_store_dwordx4 v173, v[144:147], s[98:99] offset:16
	s_waitcnt vmcnt(62)
	v_lshlrev_b32_e32 v148, 16, v128
	v_and_b32_e32 v149, 0xffff0000, v128
	v_lshlrev_b32_e32 v150, 16, v129
	v_and_b32_e32 v151, 0xffff0000, v129
	v_lshlrev_b32_e32 v152, 16, v130
	v_and_b32_e32 v153, 0xffff0000, v130
	v_lshlrev_b32_e32 v154, 16, v131
	v_and_b32_e32 v155, 0xffff0000, v131
	global_store_dwordx4 v173, v[148:151], s[100:101]
	global_store_dwordx4 v173, v[152:155], s[100:101] offset:16
.Lcc_done:
	s_branch .LBB0_518
